# conv+SwiGLU loop: hoisted the 16 row loads of the unrolled body with counted vmcnt waits (on top of batched mode-6 epilogue and rescale)
# speedup vs baseline: 1.0076x; 1.0076x over previous
; DEVI float bf_lo(unsigned u) { return __uint_as_float(u << 16); }
; DEVI float bf_hi(unsigned u) { return __uint_as_float(u & 0xffff0000u); }
; DEVI float sigmoidf_(float x) { return 1.f / (1.f + __expf(-x)); }
; DEVI void st_bf4(bf16_t* p, f32x4 v) { u32x2 u; u.x = cvt_pk_bf16(v[0], v[1]); u.y = cvt_pk_bf16(v[2], v[3]); *(u32x2*)p = u; }
; __device__ void phase_conv(const Params& P, int l) {
;     ...
;     for (int t = 0; t < RC; ++t) {
;       const u32x2 gr = __builtin_nontemporal_load((const u32x2*)(up + (size_t)t * 11264)), vr = __builtin_nontemporal_load((const u32x2*)(up + (size_t)t * 11264 + DFF));
;       const f32x4 g0 = {bf_lo(gr.x), bf_hi(gr.x), bf_lo(gr.y), bf_hi(gr.y)}, v0 = {bf_lo(vr.x), bf_hi(vr.x), bf_lo(vr.y), bf_hi(vr.y)};
;       const f32x4 cgv = bg + wg2 * g0 + wg1 * g1 + wg0 * g2;
;       const f32x4 cvv = bv + wv2 * v0 + wv1 * v1 + wv0 * v2;
;       f32x4 o;
; #pragma unroll
;       for (int e = 0; e < 4; ++e) o[e] = cgv[e] * sigmoidf_(cgv[e]) * cvv[e];
;       st_bf4(ao + (size_t)t * DFF, o);
;       g2 = g1; g1 = g0; v2 = v1; v1 = v0;
.LBB0_28:
	v_lshl_add_u64 v[48:49], v[44:45], 0, v[36:37]
	v_add_co_u32_e32 v112, vcc, 0x1445c000, v48
	s_nop 0
	v_addc_co_u32_e32 v113, vcc, 0, v49, vcc
	global_load_dwordx2 v[80:81], v[112:113], off nt
	v_add_co_u32_e32 v112, vcc, 0x1445e000, v48
	s_nop 0
	v_addc_co_u32_e32 v113, vcc, 0, v49, vcc
	global_load_dwordx2 v[82:83], v[112:113], off offset:3072 nt
	v_add_co_u32_e32 v112, vcc, 0x14461000, v48
	s_nop 0
	v_addc_co_u32_e32 v113, vcc, 0, v49, vcc
	global_load_dwordx2 v[84:85], v[112:113], off offset:2048 nt
	v_add_co_u32_e32 v112, vcc, 0x14464000, v48
	s_nop 0
	v_addc_co_u32_e32 v113, vcc, 0, v49, vcc
	global_load_dwordx2 v[86:87], v[112:113], off offset:1024 nt
	v_add_co_u32_e32 v112, vcc, 0x14467000, v48
	s_nop 0
	v_addc_co_u32_e32 v113, vcc, 0, v49, vcc
	global_load_dwordx2 v[88:89], v[112:113], off nt
	v_add_co_u32_e32 v112, vcc, 0x14469000, v48
	s_nop 0
	v_addc_co_u32_e32 v113, vcc, 0, v49, vcc
	global_load_dwordx2 v[90:91], v[112:113], off offset:3072 nt
	v_add_co_u32_e32 v112, vcc, 0x1446c000, v48
	s_nop 0
	v_addc_co_u32_e32 v113, vcc, 0, v49, vcc
	global_load_dwordx2 v[92:93], v[112:113], off offset:2048 nt
	v_add_co_u32_e32 v112, vcc, 0x1446f000, v48
	s_nop 0
	v_addc_co_u32_e32 v113, vcc, 0, v49, vcc
	global_load_dwordx2 v[94:95], v[112:113], off offset:1024 nt
	v_add_co_u32_e32 v112, vcc, 0x14472000, v48
	s_nop 0
	v_addc_co_u32_e32 v113, vcc, 0, v49, vcc
	global_load_dwordx2 v[96:97], v[112:113], off nt
	v_add_co_u32_e32 v112, vcc, 0x14474000, v48
	s_nop 0
	v_addc_co_u32_e32 v113, vcc, 0, v49, vcc
	global_load_dwordx2 v[98:99], v[112:113], off offset:3072 nt
	v_add_co_u32_e32 v112, vcc, 0x14477000, v48
	s_nop 0
	v_addc_co_u32_e32 v113, vcc, 0, v49, vcc
	global_load_dwordx2 v[100:101], v[112:113], off offset:2048 nt
	v_add_co_u32_e32 v112, vcc, 0x1447a000, v48
	s_nop 0
	v_addc_co_u32_e32 v113, vcc, 0, v49, vcc
	global_load_dwordx2 v[102:103], v[112:113], off offset:1024 nt
	v_add_co_u32_e32 v112, vcc, 0x1447d000, v48
	s_nop 0
	v_addc_co_u32_e32 v113, vcc, 0, v49, vcc
	global_load_dwordx2 v[104:105], v[112:113], off nt
	v_add_co_u32_e32 v112, vcc, 0x1447f000, v48
	s_nop 0
	v_addc_co_u32_e32 v113, vcc, 0, v49, vcc
	global_load_dwordx2 v[106:107], v[112:113], off offset:3072 nt
	v_add_co_u32_e32 v112, vcc, 0x14482000, v48
	s_nop 0
	v_addc_co_u32_e32 v113, vcc, 0, v49, vcc
	global_load_dwordx2 v[108:109], v[112:113], off offset:2048 nt
	v_add_co_u32_e32 v112, vcc, 0x14485000, v48
	s_nop 0
	v_addc_co_u32_e32 v113, vcc, 0, v49, vcc
	global_load_dwordx2 v[110:111], v[112:113], off offset:1024 nt
	v_add_co_u32_e32 v60, vcc, 0x1445c000, v48
	v_mov_b32_e32 v66, v32
	s_nop 0
	v_addc_co_u32_e32 v61, vcc, 0, v49, vcc
	v_add_co_u32_e32 v62, vcc, 0x1445e000, v48
	s_nop 0
	v_addc_co_u32_e32 v63, vcc, 0, v49, vcc
	v_mov_b32_e32 v67, v24
	v_mov_b32_e32 v70, v28
	v_mov_b32_e32 v71, v20
	s_mov_b32 s3, 0x1f45c000
	s_add_i32 s2, s2, -8
	s_cmp_eq_u32 s2, 0
	s_waitcnt vmcnt(15)
	v_lshlrev_b32_e32 v63, 16, v80
	s_waitcnt vmcnt(14)
	v_lshlrev_b32_e32 v62, 16, v82
	v_pk_fma_f32 v[64:65], v[50:51], v[62:63], v[46:47]
	s_nop 0
	v_pk_fma_f32 v[64:65], v[42:43], v[66:67], v[64:65]
	s_nop 0
	v_pk_fma_f32 v[64:65], v[38:39], v[70:71], v[64:65]
	s_nop 0
	v_mul_f32_e32 v0, 0xbfb8aa3b, v65
	v_exp_f32_e32 v0, v0
	s_nop 0
	v_add_f32_e32 v0, 1.0, v0
	v_div_scale_f32 v20, s[6:7], v0, v0, 1.0
	v_rcp_f32_e32 v24, v20
	s_nop 0
	v_fma_f32 v28, -v20, v24, 1.0
	v_fmac_f32_e32 v24, v28, v24
	v_div_scale_f32 v28, vcc, 1.0, v0, 1.0
	v_mul_f32_e32 v32, v28, v24
	v_fma_f32 v70, -v20, v32, v28
	v_fmac_f32_e32 v32, v70, v24
	v_fma_f32 v20, -v20, v32, v28
	v_div_fmas_f32 v20, v20, v24, v32
	v_div_fixup_f32 v0, v20, v0, 1.0
	v_mul_f32_e32 v0, v65, v0
	v_mul_f32_e32 v0, v64, v0
	v_and_b32_e32 v65, 0xffff0000, v80
	v_and_b32_e32 v64, 0xffff0000, v82
	v_pk_fma_f32 v[70:71], v[12:13], v[64:65], v[16:17]
	v_mov_b32_e32 v24, v33
	v_pk_fma_f32 v[32:33], v[8:9], v[24:25], v[70:71]
	v_mov_b32_e32 v20, v29
	v_pk_fma_f32 v[20:21], v[4:5], v[20:21], v[32:33]
	v_mov_b32_e32 v70, v30
	v_mul_f32_e32 v28, 0xbfb8aa3b, v21
	v_exp_f32_e32 v28, v28
	v_mov_b32_e32 v71, v22
	v_add_f32_e32 v28, 1.0, v28
	v_div_scale_f32 v29, s[6:7], v28, v28, 1.0
	v_rcp_f32_e32 v32, v29
	s_nop 0
	v_fma_f32 v33, -v29, v32, 1.0
	v_fmac_f32_e32 v32, v33, v32
	v_div_scale_f32 v33, vcc, 1.0, v28, 1.0
	v_mul_f32_e32 v60, v33, v32
	v_fma_f32 v68, -v29, v60, v33
	v_fmac_f32_e32 v60, v68, v32
	v_fma_f32 v29, -v29, v60, v33
	v_div_fmas_f32 v29, v29, v32, v60
	v_div_fixup_f32 v28, v29, v28, 1.0
	v_mul_f32_e32 v21, v21, v28
	v_mul_f32_e32 v68, v20, v21
	v_lshlrev_b32_e32 v21, 16, v81
	v_lshlrev_b32_e32 v20, 16, v83
	v_pk_fma_f32 v[28:29], v[58:59], v[20:21], v[56:57]
	v_mov_b32_e32 v32, v34
	v_mov_b32_e32 v33, v26
	v_pk_fma_f32 v[28:29], v[54:55], v[32:33], v[28:29]
	s_nop 0
	v_pk_fma_f32 v[28:29], v[2:3], v[70:71], v[28:29]
	s_nop 0
	v_mul_f32_e32 v22, 0xbfb8aa3b, v29
	v_exp_f32_e32 v22, v22
	s_nop 0
	v_add_f32_e32 v22, 1.0, v22
	v_div_scale_f32 v26, s[6:7], v22, v22, 1.0
	v_rcp_f32_e32 v30, v26
	s_nop 0
	v_fma_f32 v34, -v26, v30, 1.0
	v_fmac_f32_e32 v30, v34, v30
	v_div_scale_f32 v34, vcc, 1.0, v22, 1.0
	v_mul_f32_e32 v60, v34, v30
	v_fma_f32 v70, -v26, v60, v34
	v_fmac_f32_e32 v60, v70, v30
	v_fma_f32 v26, -v26, v60, v34
	v_div_fmas_f32 v26, v26, v30, v60
	v_div_fixup_f32 v22, v26, v22, 1.0
	v_mul_f32_e32 v22, v29, v22
	v_mul_f32_e32 v30, v28, v22
	v_and_b32_e32 v29, 0xffff0000, v81
	v_and_b32_e32 v28, 0xffff0000, v83
	v_pk_fma_f32 v[60:61], v[14:15], v[28:29], v[18:19]
	v_mov_b32_e32 v26, v35
	v_pk_fma_f32 v[34:35], v[10:11], v[26:27], v[60:61]
	v_mov_b32_e32 v22, v31
	v_pk_fma_f32 v[22:23], v[6:7], v[22:23], v[34:35]
	s_nop 0
	v_mul_f32_e32 v31, 0xbfb8aa3b, v23
	v_exp_f32_e32 v31, v31
	s_nop 0
	v_add_f32_e32 v31, 1.0, v31
	v_div_scale_f32 v34, s[6:7], v31, v31, 1.0
	v_rcp_f32_e32 v35, v34
	s_nop 0
	v_fma_f32 v60, -v34, v35, 1.0
	v_fmac_f32_e32 v35, v60, v35
	v_div_scale_f32 v60, vcc, 1.0, v31, 1.0
	v_mul_f32_e32 v61, v60, v35
	v_fma_f32 v69, -v34, v61, v60
	v_fmac_f32_e32 v61, v69, v35
	v_fma_f32 v34, -v34, v61, v60
	v_div_fmas_f32 v34, v34, v35, v61
	v_div_fixup_f32 v31, v34, v31, 1.0
	v_mul_f32_e32 v23, v23, v31
	v_mul_f32_e32 v23, v22, v23
	v_lshl_add_u64 v[60:61], v[40:41], 0, v[36:37]
	v_cvt_pk_bf16_f32 v23, v30, v23
	v_add_co_u32_e32 v30, vcc, s3, v60
	v_cvt_pk_bf16_f32 v22, v0, v68
	s_mov_b32 s3, 0x14461000
	s_nop 0
	v_addc_co_u32_e32 v31, vcc, 0, v61, vcc
	global_store_dwordx2 v[30:31], v[22:23], off
	v_add_co_u32_e32 v22, vcc, s3, v48
	s_mov_b32 s3, 0x14464000
	s_nop 0
	v_addc_co_u32_e32 v23, vcc, 0, v49, vcc
	v_add_co_u32_e32 v22, vcc, s3, v48
	s_mov_b32 s3, 0x1f45e000
	s_nop 0
	v_addc_co_u32_e32 v23, vcc, 0, v49, vcc
	s_waitcnt vmcnt(14)
; DEVI float bf_lo(unsigned u) { return __uint_as_float(u << 16); }
; DEVI float bf_hi(unsigned u) { return __uint_as_float(u & 0xffff0000u); }
; DEVI float sigmoidf_(float x) { return 1.f / (1.f + __expf(-x)); }
; DEVI void st_bf4(bf16_t* p, f32x4 v) { u32x2 u; u.x = cvt_pk_bf16(v[0], v[1]); u.y = cvt_pk_bf16(v[2], v[3]); *(u32x2*)p = u; }
; __device__ void phase_conv(const Params& P, int l) {
;     ...
;     for (int t = 0; t < RC; ++t) {
;       const u32x2 gr = __builtin_nontemporal_load((const u32x2*)(up + (size_t)t * 11264)), vr = __builtin_nontemporal_load((const u32x2*)(up + (size_t)t * 11264 + DFF));
;       const f32x4 g0 = {bf_lo(gr.x), bf_hi(gr.x), bf_lo(gr.y), bf_hi(gr.y)}, v0 = {bf_lo(vr.x), bf_hi(vr.x), bf_lo(vr.y), bf_hi(vr.y)};
;       const f32x4 cgv = bg + wg2 * g0 + wg1 * g1 + wg0 * g2;
;       const f32x4 cvv = bv + wv2 * v0 + wv1 * v1 + wv0 * v2;
;       f32x4 o;
; #pragma unroll
;       for (int e = 0; e < 4; ++e) o[e] = cgv[e] * sigmoidf_(cgv[e]) * cvv[e];
;       st_bf4(ao + (size_t)t * DFF, o);
;       g2 = g1; g1 = g0; v2 = v1; v1 = v0;
	v_lshlrev_b32_e32 v71, 16, v84
	s_waitcnt vmcnt(13)
	v_lshlrev_b32_e32 v70, 16, v86
	v_pk_fma_f32 v[22:23], v[50:51], v[70:71], v[46:47]
	s_nop 0
	v_pk_fma_f32 v[22:23], v[42:43], v[62:63], v[22:23]
	s_nop 0
	v_pk_fma_f32 v[22:23], v[38:39], v[66:67], v[22:23]
	s_nop 0
	v_mul_f32_e32 v0, 0xbfb8aa3b, v23
	v_exp_f32_e32 v0, v0
	s_nop 0
	v_add_f32_e32 v0, 1.0, v0
	v_div_scale_f32 v34, s[6:7], v0, v0, 1.0
	v_rcp_f32_e32 v35, v34
	s_nop 0
	v_fma_f32 v66, -v34, v35, 1.0
	v_fmac_f32_e32 v35, v66, v35
	v_div_scale_f32 v66, vcc, 1.0, v0, 1.0
	v_mul_f32_e32 v67, v66, v35
	v_fma_f32 v74, -v34, v67, v66
	v_fmac_f32_e32 v67, v74, v35
	v_fma_f32 v34, -v34, v67, v66
	v_div_fmas_f32 v34, v34, v35, v67
	v_div_fixup_f32 v0, v34, v0, 1.0
	v_mul_f32_e32 v0, v23, v0
	v_mul_f32_e32 v0, v22, v0
	v_and_b32_e32 v23, 0xffff0000, v84
	v_and_b32_e32 v22, 0xffff0000, v86
	v_pk_fma_f32 v[34:35], v[12:13], v[22:23], v[16:17]
	s_nop 0
	v_pk_fma_f32 v[34:35], v[8:9], v[64:65], v[34:35]
	s_nop 0
	v_pk_fma_f32 v[24:25], v[4:5], v[24:25], v[34:35]
	s_nop 0
	v_mul_f32_e32 v30, 0xbfb8aa3b, v25
	v_exp_f32_e32 v30, v30
	s_nop 0
	v_add_f32_e32 v30, 1.0, v30
	v_div_scale_f32 v34, s[6:7], v30, v30, 1.0
	v_rcp_f32_e32 v35, v34
	s_nop 0
	v_fma_f32 v66, -v34, v35, 1.0
	v_fmac_f32_e32 v35, v66, v35
	v_div_scale_f32 v66, vcc, 1.0, v30, 1.0
	v_mul_f32_e32 v67, v66, v35
	v_fma_f32 v68, -v34, v67, v66
	v_fmac_f32_e32 v67, v68, v35
	v_fma_f32 v34, -v34, v67, v66
	v_div_fmas_f32 v34, v34, v35, v67
	v_div_fixup_f32 v30, v34, v30, 1.0
	v_mul_f32_e32 v25, v25, v30
	v_lshlrev_b32_e32 v35, 16, v85
	v_lshlrev_b32_e32 v34, 16, v87
	v_mul_f32_e32 v66, v24, v25
	v_pk_fma_f32 v[24:25], v[58:59], v[34:35], v[56:57]
	s_nop 0
	v_pk_fma_f32 v[24:25], v[54:55], v[20:21], v[24:25]
	s_nop 0
	v_pk_fma_f32 v[24:25], v[2:3], v[32:33], v[24:25]
	s_nop 0
	v_mul_f32_e32 v30, 0xbfb8aa3b, v25
	v_exp_f32_e32 v30, v30
	s_nop 0
	v_add_f32_e32 v30, 1.0, v30
	v_div_scale_f32 v32, s[6:7], v30, v30, 1.0
	v_rcp_f32_e32 v33, v32
	s_nop 0
	v_fma_f32 v67, -v32, v33, 1.0
	v_fmac_f32_e32 v33, v67, v33
	v_div_scale_f32 v67, vcc, 1.0, v30, 1.0
	v_mul_f32_e32 v68, v67, v33
	v_fma_f32 v74, -v32, v68, v67
	v_fmac_f32_e32 v68, v74, v33
	v_fma_f32 v32, -v32, v68, v67
	v_div_fmas_f32 v32, v32, v33, v68
	v_div_fixup_f32 v30, v32, v30, 1.0
	v_mul_f32_e32 v25, v25, v30
	v_mul_f32_e32 v32, v24, v25
	v_and_b32_e32 v25, 0xffff0000, v85
	v_and_b32_e32 v24, 0xffff0000, v87
	v_pk_fma_f32 v[30:31], v[14:15], v[24:25], v[18:19]
	s_nop 0
	v_pk_fma_f32 v[30:31], v[10:11], v[28:29], v[30:31]
	s_nop 0
	v_pk_fma_f32 v[26:27], v[6:7], v[26:27], v[30:31]
	s_nop 0
	v_mul_f32_e32 v30, 0xbfb8aa3b, v27
	v_exp_f32_e32 v30, v30
	s_nop 0
	v_add_f32_e32 v30, 1.0, v30
	v_div_scale_f32 v31, s[6:7], v30, v30, 1.0
	v_rcp_f32_e32 v33, v31
	s_nop 0
	v_fma_f32 v67, -v31, v33, 1.0
	v_fmac_f32_e32 v33, v67, v33
	v_div_scale_f32 v67, vcc, 1.0, v30, 1.0
	v_mul_f32_e32 v68, v67, v33
	v_fma_f32 v69, -v31, v68, v67
	v_fmac_f32_e32 v68, v69, v33
	v_fma_f32 v31, -v31, v68, v67
	v_div_fmas_f32 v31, v31, v33, v68
	v_div_fixup_f32 v30, v31, v30, 1.0
	v_mul_f32_e32 v27, v27, v30
	v_add_co_u32_e32 v30, vcc, s3, v60
	v_mul_f32_e32 v27, v26, v27
	v_cvt_pk_bf16_f32 v26, v0, v66
	s_nop 0
	v_addc_co_u32_e32 v31, vcc, 0, v61, vcc
	s_mov_b32 s3, 0x14467000
	v_cvt_pk_bf16_f32 v27, v32, v27
	global_store_dwordx2 v[30:31], v[26:27], off offset:3072
	v_add_co_u32_e32 v26, vcc, s3, v48
	s_mov_b32 s3, 0x14469000
	s_nop 0
	v_addc_co_u32_e32 v27, vcc, 0, v49, vcc
	v_add_co_u32_e32 v26, vcc, s3, v48
	s_mov_b32 s3, 0x1f461000
	s_nop 0
	v_addc_co_u32_e32 v27, vcc, 0, v49, vcc
	s_waitcnt vmcnt(13)
	v_lshlrev_b32_e32 v31, 16, v88
	s_waitcnt vmcnt(12)
	v_lshlrev_b32_e32 v30, 16, v90
	v_pk_fma_f32 v[26:27], v[50:51], v[30:31], v[46:47]
	s_nop 0
	v_pk_fma_f32 v[26:27], v[42:43], v[70:71], v[26:27]
	s_nop 0
	v_pk_fma_f32 v[26:27], v[38:39], v[62:63], v[26:27]
	s_nop 0
	v_mul_f32_e32 v0, 0xbfb8aa3b, v27
	v_exp_f32_e32 v0, v0
	s_nop 0
	v_add_f32_e32 v0, 1.0, v0
	v_div_scale_f32 v32, s[6:7], v0, v0, 1.0
	v_rcp_f32_e32 v33, v32
	s_nop 0
	v_fma_f32 v62, -v32, v33, 1.0
	v_fmac_f32_e32 v33, v62, v33
	v_div_scale_f32 v62, vcc, 1.0, v0, 1.0
	v_mul_f32_e32 v63, v62, v33
	v_fma_f32 v74, -v32, v63, v62
	v_fmac_f32_e32 v63, v74, v33
	v_fma_f32 v32, -v32, v63, v62
	v_div_fmas_f32 v32, v32, v33, v63
	v_div_fixup_f32 v0, v32, v0, 1.0
	v_mul_f32_e32 v0, v27, v0
	v_mul_f32_e32 v0, v26, v0
	v_and_b32_e32 v27, 0xffff0000, v88
	v_and_b32_e32 v26, 0xffff0000, v90
	v_pk_fma_f32 v[32:33], v[12:13], v[26:27], v[16:17]
	s_nop 0
	v_pk_fma_f32 v[32:33], v[8:9], v[22:23], v[32:33]
	s_nop 0
	v_pk_fma_f32 v[32:33], v[4:5], v[64:65], v[32:33]
	s_nop 0
	v_mul_f32_e32 v62, 0xbfb8aa3b, v33
	v_exp_f32_e32 v62, v62
	s_nop 0
	v_add_f32_e32 v62, 1.0, v62
	v_div_scale_f32 v63, s[6:7], v62, v62, 1.0
	v_rcp_f32_e32 v64, v63
	s_nop 0
	v_fma_f32 v65, -v63, v64, 1.0
	v_fmac_f32_e32 v64, v65, v64
	v_div_scale_f32 v65, vcc, 1.0, v62, 1.0
	v_mul_f32_e32 v66, v65, v64
	v_fma_f32 v68, -v63, v66, v65
	v_fmac_f32_e32 v66, v68, v64
	v_fma_f32 v63, -v63, v66, v65
	v_div_fmas_f32 v63, v63, v64, v66
	v_div_fixup_f32 v62, v63, v62, 1.0
	v_mul_f32_e32 v33, v33, v62
	v_mul_f32_e32 v64, v32, v33
	v_lshlrev_b32_e32 v33, 16, v89
	v_lshlrev_b32_e32 v32, 16, v91
	v_pk_fma_f32 v[62:63], v[58:59], v[32:33], v[56:57]
	s_nop 0
	v_pk_fma_f32 v[62:63], v[54:55], v[34:35], v[62:63]
	s_nop 0
	v_pk_fma_f32 v[20:21], v[2:3], v[20:21], v[62:63]
	s_nop 0
	v_mul_f32_e32 v62, 0xbfb8aa3b, v21
	v_exp_f32_e32 v62, v62
	s_nop 0
	v_add_f32_e32 v62, 1.0, v62
	v_div_scale_f32 v63, s[6:7], v62, v62, 1.0
	v_rcp_f32_e32 v65, v63
	s_nop 0
	v_fma_f32 v66, -v63, v65, 1.0
	v_fmac_f32_e32 v65, v66, v65
; DEVI float bf_lo(unsigned u) { return __uint_as_float(u << 16); }
; DEVI float bf_hi(unsigned u) { return __uint_as_float(u & 0xffff0000u); }
; DEVI float sigmoidf_(float x) { return 1.f / (1.f + __expf(-x)); }
; DEVI void st_bf4(bf16_t* p, f32x4 v) { u32x2 u; u.x = cvt_pk_bf16(v[0], v[1]); u.y = cvt_pk_bf16(v[2], v[3]); *(u32x2*)p = u; }
; __device__ void phase_conv(const Params& P, int l) {
;     ...
;     for (int t = 0; t < RC; ++t) {
;       const u32x2 gr = __builtin_nontemporal_load((const u32x2*)(up + (size_t)t * 11264)), vr = __builtin_nontemporal_load((const u32x2*)(up + (size_t)t * 11264 + DFF));
;       const f32x4 g0 = {bf_lo(gr.x), bf_hi(gr.x), bf_lo(gr.y), bf_hi(gr.y)}, v0 = {bf_lo(vr.x), bf_hi(vr.x), bf_lo(vr.y), bf_hi(vr.y)};
;       const f32x4 cgv = bg + wg2 * g0 + wg1 * g1 + wg0 * g2;
;       const f32x4 cvv = bv + wv2 * v0 + wv1 * v1 + wv0 * v2;
;       f32x4 o;
; #pragma unroll
;       for (int e = 0; e < 4; ++e) o[e] = cgv[e] * sigmoidf_(cgv[e]) * cvv[e];
;       st_bf4(ao + (size_t)t * DFF, o);
;       g2 = g1; g1 = g0; v2 = v1; v1 = v0;
	v_div_scale_f32 v66, vcc, 1.0, v62, 1.0
	v_mul_f32_e32 v68, v66, v65
	v_fma_f32 v74, -v63, v68, v66
	v_fmac_f32_e32 v68, v74, v65
	v_fma_f32 v63, -v63, v68, v66
	v_div_fmas_f32 v63, v63, v65, v68
	v_div_fixup_f32 v62, v63, v62, 1.0
	v_mul_f32_e32 v21, v21, v62
	v_mul_f32_e32 v65, v20, v21
	v_and_b32_e32 v21, 0xffff0000, v89
	v_and_b32_e32 v20, 0xffff0000, v91
	v_pk_fma_f32 v[62:63], v[14:15], v[20:21], v[18:19]
	s_nop 0
	v_pk_fma_f32 v[62:63], v[10:11], v[24:25], v[62:63]
	s_nop 0
	v_pk_fma_f32 v[28:29], v[6:7], v[28:29], v[62:63]
	s_nop 0
	v_mul_f32_e32 v62, 0xbfb8aa3b, v29
	v_exp_f32_e32 v62, v62
	s_nop 0
	v_add_f32_e32 v62, 1.0, v62
	v_div_scale_f32 v63, s[6:7], v62, v62, 1.0
	v_rcp_f32_e32 v66, v63
	s_nop 0
	v_fma_f32 v67, -v63, v66, 1.0
	v_fmac_f32_e32 v66, v67, v66
	v_div_scale_f32 v67, vcc, 1.0, v62, 1.0
	v_mul_f32_e32 v68, v67, v66
	v_fma_f32 v69, -v63, v68, v67
	v_fmac_f32_e32 v68, v69, v66
	v_fma_f32 v63, -v63, v68, v67
	v_div_fmas_f32 v63, v63, v66, v68
	v_div_fixup_f32 v62, v63, v62, 1.0
	v_mul_f32_e32 v29, v29, v62
	v_add_co_u32_e32 v62, vcc, s3, v60
	v_mul_f32_e32 v29, v28, v29
	v_cvt_pk_bf16_f32 v28, v0, v64
	s_nop 0
	v_addc_co_u32_e32 v63, vcc, 0, v61, vcc
	s_mov_b32 s3, 0x1446c000
	v_cvt_pk_bf16_f32 v29, v65, v29
	global_store_dwordx2 v[62:63], v[28:29], off offset:2048
	v_add_co_u32_e32 v28, vcc, s3, v48
	s_mov_b32 s3, 0x1446f000
	s_nop 0
	v_addc_co_u32_e32 v29, vcc, 0, v49, vcc
	v_add_co_u32_e32 v28, vcc, s3, v48
	s_mov_b32 s3, 0x1f464000
	s_nop 0
	v_addc_co_u32_e32 v29, vcc, 0, v49, vcc
	s_waitcnt vmcnt(12)
	v_lshlrev_b32_e32 v69, 16, v92
	s_waitcnt vmcnt(11)
	v_lshlrev_b32_e32 v68, 16, v94
	v_pk_fma_f32 v[28:29], v[50:51], v[68:69], v[46:47]
	s_nop 0
	v_pk_fma_f32 v[28:29], v[42:43], v[30:31], v[28:29]
	s_nop 0
	v_pk_fma_f32 v[28:29], v[38:39], v[70:71], v[28:29]
	s_nop 0
	v_mul_f32_e32 v0, 0xbfb8aa3b, v29
	v_exp_f32_e32 v0, v0
	s_nop 0
	v_add_f32_e32 v0, 1.0, v0
	v_div_scale_f32 v62, s[6:7], v0, v0, 1.0
	v_rcp_f32_e32 v63, v62
	s_nop 0
	v_fma_f32 v70, -v62, v63, 1.0
	v_fmac_f32_e32 v63, v70, v63
	v_div_scale_f32 v70, vcc, 1.0, v0, 1.0
	v_mul_f32_e32 v71, v70, v63
	v_fma_f32 v74, -v62, v71, v70
	v_fmac_f32_e32 v71, v74, v63
	v_fma_f32 v62, -v62, v71, v70
	v_div_fmas_f32 v62, v62, v63, v71
	v_div_fixup_f32 v0, v62, v0, 1.0
	v_mul_f32_e32 v0, v29, v0
	v_mul_f32_e32 v0, v28, v0
	v_and_b32_e32 v29, 0xffff0000, v92
	v_and_b32_e32 v28, 0xffff0000, v94
	v_pk_fma_f32 v[62:63], v[12:13], v[28:29], v[16:17]
	s_nop 0
	v_pk_fma_f32 v[62:63], v[8:9], v[26:27], v[62:63]
	s_nop 0
	v_pk_fma_f32 v[22:23], v[4:5], v[22:23], v[62:63]
	s_nop 0
	v_mul_f32_e32 v62, 0xbfb8aa3b, v23
	v_exp_f32_e32 v62, v62
	s_nop 0
	v_add_f32_e32 v62, 1.0, v62
	v_div_scale_f32 v63, s[6:7], v62, v62, 1.0
	v_rcp_f32_e32 v64, v63
	s_nop 0
	v_fma_f32 v66, -v63, v64, 1.0
	v_fmac_f32_e32 v64, v66, v64
	v_div_scale_f32 v66, vcc, 1.0, v62, 1.0
	v_mul_f32_e32 v70, v66, v64
	v_fma_f32 v71, -v63, v70, v66
	v_fmac_f32_e32 v70, v71, v64
	v_fma_f32 v63, -v63, v70, v66
	v_div_fmas_f32 v63, v63, v64, v70
	v_div_fixup_f32 v62, v63, v62, 1.0
	v_mul_f32_e32 v23, v23, v62
	v_lshlrev_b32_e32 v63, 16, v93
	v_lshlrev_b32_e32 v62, 16, v95
	v_mul_f32_e32 v64, v22, v23
	v_pk_fma_f32 v[22:23], v[58:59], v[62:63], v[56:57]
	s_nop 0
	v_pk_fma_f32 v[22:23], v[54:55], v[32:33], v[22:23]
	s_nop 0
	v_pk_fma_f32 v[22:23], v[2:3], v[34:35], v[22:23]
	s_nop 0
	v_mul_f32_e32 v34, 0xbfb8aa3b, v23
	v_exp_f32_e32 v34, v34
	s_nop 0
	v_add_f32_e32 v34, 1.0, v34
	v_div_scale_f32 v35, s[6:7], v34, v34, 1.0
	v_rcp_f32_e32 v66, v35
	s_nop 0
	v_fma_f32 v70, -v35, v66, 1.0
	v_fmac_f32_e32 v66, v70, v66
	v_div_scale_f32 v70, vcc, 1.0, v34, 1.0
	v_mul_f32_e32 v71, v70, v66
	v_fma_f32 v74, -v35, v71, v70
	v_fmac_f32_e32 v71, v74, v66
	v_fma_f32 v35, -v35, v71, v70
	v_div_fmas_f32 v35, v35, v66, v71
	v_div_fixup_f32 v34, v35, v34, 1.0
	v_mul_f32_e32 v23, v23, v34
	v_mul_f32_e32 v66, v22, v23
	v_and_b32_e32 v23, 0xffff0000, v93
	v_and_b32_e32 v22, 0xffff0000, v95
	v_pk_fma_f32 v[34:35], v[14:15], v[22:23], v[18:19]
	s_nop 0
	v_pk_fma_f32 v[34:35], v[10:11], v[20:21], v[34:35]
	s_nop 0
	v_pk_fma_f32 v[24:25], v[6:7], v[24:25], v[34:35]
	s_nop 0
	v_mul_f32_e32 v34, 0xbfb8aa3b, v25
	v_exp_f32_e32 v34, v34
	s_nop 0
	v_add_f32_e32 v34, 1.0, v34
	v_div_scale_f32 v35, s[6:7], v34, v34, 1.0
	v_rcp_f32_e32 v65, v35
	s_nop 0
	v_fma_f32 v67, -v35, v65, 1.0
	v_fmac_f32_e32 v65, v67, v65
	v_div_scale_f32 v67, vcc, 1.0, v34, 1.0
	v_mul_f32_e32 v70, v67, v65
	v_fma_f32 v71, -v35, v70, v67
	v_fmac_f32_e32 v70, v71, v65
	v_fma_f32 v35, -v35, v70, v67
	v_div_fmas_f32 v35, v35, v65, v70
	v_div_fixup_f32 v34, v35, v34, 1.0
	v_mul_f32_e32 v25, v25, v34
	v_add_co_u32_e32 v34, vcc, s3, v60
	v_mul_f32_e32 v25, v24, v25
	v_cvt_pk_bf16_f32 v24, v0, v64
	s_nop 0
	v_addc_co_u32_e32 v35, vcc, 0, v61, vcc
	s_mov_b32 s3, 0x14472000
	v_cvt_pk_bf16_f32 v25, v66, v25
	global_store_dwordx2 v[34:35], v[24:25], off offset:1024
	v_add_co_u32_e32 v24, vcc, s3, v48
	s_mov_b32 s3, 0x14474000
	s_nop 0
	v_addc_co_u32_e32 v25, vcc, 0, v49, vcc
	v_add_co_u32_e32 v34, vcc, s3, v48
	s_nop 0
	v_addc_co_u32_e32 v35, vcc, 0, v49, vcc
	s_mov_b32 s3, 0x1f467000
	s_waitcnt vmcnt(11)
	v_lshlrev_b32_e32 v67, 16, v96
	s_waitcnt vmcnt(10)
; DEVI float bf_lo(unsigned u) { return __uint_as_float(u << 16); }
; DEVI float bf_hi(unsigned u) { return __uint_as_float(u & 0xffff0000u); }
; DEVI float sigmoidf_(float x) { return 1.f / (1.f + __expf(-x)); }
; DEVI void st_bf4(bf16_t* p, f32x4 v) { u32x2 u; u.x = cvt_pk_bf16(v[0], v[1]); u.y = cvt_pk_bf16(v[2], v[3]); *(u32x2*)p = u; }
; __device__ void phase_conv(const Params& P, int l) {
;     ...
;     for (int t = 0; t < RC; ++t) {
;       const u32x2 gr = __builtin_nontemporal_load((const u32x2*)(up + (size_t)t * 11264)), vr = __builtin_nontemporal_load((const u32x2*)(up + (size_t)t * 11264 + DFF));
;       const f32x4 g0 = {bf_lo(gr.x), bf_hi(gr.x), bf_lo(gr.y), bf_hi(gr.y)}, v0 = {bf_lo(vr.x), bf_hi(vr.x), bf_lo(vr.y), bf_hi(vr.y)};
;       const f32x4 cgv = bg + wg2 * g0 + wg1 * g1 + wg0 * g2;
;       const f32x4 cvv = bv + wv2 * v0 + wv1 * v1 + wv0 * v2;
;       f32x4 o;
; #pragma unroll
;       for (int e = 0; e < 4; ++e) o[e] = cgv[e] * sigmoidf_(cgv[e]) * cvv[e];
;       st_bf4(ao + (size_t)t * DFF, o);
;       g2 = g1; g1 = g0; v2 = v1; v1 = v0;
	v_lshlrev_b32_e32 v66, 16, v98
	v_pk_fma_f32 v[64:65], v[50:51], v[66:67], v[46:47]
	s_nop 0
	v_pk_fma_f32 v[64:65], v[42:43], v[68:69], v[64:65]
	s_nop 0
	v_pk_fma_f32 v[30:31], v[38:39], v[30:31], v[64:65]
	s_nop 0
	v_mul_f32_e32 v0, 0xbfb8aa3b, v31
	v_exp_f32_e32 v0, v0
	s_nop 0
	v_add_f32_e32 v0, 1.0, v0
	v_div_scale_f32 v64, s[6:7], v0, v0, 1.0
	v_rcp_f32_e32 v65, v64
	s_nop 0
	v_fma_f32 v70, -v64, v65, 1.0
	v_fmac_f32_e32 v65, v70, v65
	v_div_scale_f32 v70, vcc, 1.0, v0, 1.0
	v_mul_f32_e32 v71, v70, v65
	v_fma_f32 v74, -v64, v71, v70
	v_fmac_f32_e32 v71, v74, v65
	v_fma_f32 v64, -v64, v71, v70
	v_div_fmas_f32 v64, v64, v65, v71
	v_div_fixup_f32 v0, v64, v0, 1.0
	v_mul_f32_e32 v0, v31, v0
	v_mul_f32_e32 v0, v30, v0
	v_and_b32_e32 v31, 0xffff0000, v96
	v_and_b32_e32 v30, 0xffff0000, v98
	v_pk_fma_f32 v[64:65], v[12:13], v[30:31], v[16:17]
	s_nop 0
	v_pk_fma_f32 v[64:65], v[8:9], v[28:29], v[64:65]
	s_nop 0
	v_pk_fma_f32 v[26:27], v[4:5], v[26:27], v[64:65]
	s_nop 0
	v_mul_f32_e32 v24, 0xbfb8aa3b, v27
	v_exp_f32_e32 v24, v24
	s_nop 0
	v_add_f32_e32 v24, 1.0, v24
	v_div_scale_f32 v34, s[6:7], v24, v24, 1.0
	v_rcp_f32_e32 v64, v34
	s_nop 0
	v_fma_f32 v65, -v34, v64, 1.0
	v_fmac_f32_e32 v64, v65, v64
	v_div_scale_f32 v65, vcc, 1.0, v24, 1.0
	v_mul_f32_e32 v70, v65, v64
	v_fma_f32 v71, -v34, v70, v65
	v_fmac_f32_e32 v70, v71, v64
	v_fma_f32 v34, -v34, v70, v65
	v_div_fmas_f32 v34, v34, v64, v70
	v_div_fixup_f32 v24, v34, v24, 1.0
	v_mul_f32_e32 v24, v27, v24
	v_lshlrev_b32_e32 v65, 16, v97
	v_lshlrev_b32_e32 v64, 16, v99
	v_mul_f32_e32 v34, v26, v24
	v_pk_fma_f32 v[26:27], v[58:59], v[64:65], v[56:57]
	s_nop 0
	v_pk_fma_f32 v[26:27], v[54:55], v[62:63], v[26:27]
	s_nop 0
	v_pk_fma_f32 v[26:27], v[2:3], v[32:33], v[26:27]
	s_nop 0
	v_mul_f32_e32 v24, 0xbfb8aa3b, v27
	v_exp_f32_e32 v24, v24
	s_nop 0
	v_add_f32_e32 v24, 1.0, v24
	v_div_scale_f32 v32, s[6:7], v24, v24, 1.0
	v_rcp_f32_e32 v33, v32
	s_nop 0
	v_fma_f32 v70, -v32, v33, 1.0
	v_fmac_f32_e32 v33, v70, v33
	v_div_scale_f32 v70, vcc, 1.0, v24, 1.0
	v_mul_f32_e32 v71, v70, v33
	v_fma_f32 v74, -v32, v71, v70
	v_fmac_f32_e32 v71, v74, v33
	v_fma_f32 v32, -v32, v71, v70
	v_div_fmas_f32 v32, v32, v33, v71
	v_div_fixup_f32 v24, v32, v24, 1.0
	v_mul_f32_e32 v24, v27, v24
	v_and_b32_e32 v33, 0xffff0000, v97
	v_and_b32_e32 v32, 0xffff0000, v99
	v_mul_f32_e32 v26, v26, v24
	v_pk_fma_f32 v[24:25], v[14:15], v[32:33], v[18:19]
	s_nop 0
	v_pk_fma_f32 v[24:25], v[10:11], v[22:23], v[24:25]
	s_nop 0
	v_pk_fma_f32 v[20:21], v[6:7], v[20:21], v[24:25]
	s_nop 0
	v_mul_f32_e32 v24, 0xbfb8aa3b, v21
	v_exp_f32_e32 v24, v24
	s_nop 0
	v_add_f32_e32 v24, 1.0, v24
	v_div_scale_f32 v25, s[6:7], v24, v24, 1.0
	v_rcp_f32_e32 v27, v25
	s_nop 0
	v_fma_f32 v35, -v25, v27, 1.0
	v_fmac_f32_e32 v27, v35, v27
	v_div_scale_f32 v35, vcc, 1.0, v24, 1.0
	v_mul_f32_e32 v70, v35, v27
	v_fma_f32 v71, -v25, v70, v35
	v_fmac_f32_e32 v70, v71, v27
	v_fma_f32 v25, -v25, v70, v35
	v_div_fmas_f32 v25, v25, v27, v70
	v_div_fixup_f32 v24, v25, v24, 1.0
	v_mul_f32_e32 v21, v21, v24
	v_add_co_u32_e32 v24, vcc, s3, v60
	v_mul_f32_e32 v21, v20, v21
	v_cvt_pk_bf16_f32 v20, v0, v34
	s_nop 0
	v_addc_co_u32_e32 v25, vcc, 0, v61, vcc
	s_mov_b32 s3, 0x14477000
	v_cvt_pk_bf16_f32 v21, v26, v21
	global_store_dwordx2 v[24:25], v[20:21], off
	v_add_co_u32_e32 v20, vcc, s3, v48
	s_mov_b32 s3, 0x1447a000
	s_nop 0
	v_addc_co_u32_e32 v21, vcc, 0, v49, vcc
	v_add_co_u32_e32 v24, vcc, s3, v48
	s_nop 0
	v_addc_co_u32_e32 v25, vcc, 0, v49, vcc
	s_mov_b32 s3, 0x1f469000
	s_waitcnt vmcnt(10)
	v_lshlrev_b32_e32 v35, 16, v100
	s_waitcnt vmcnt(9)
	v_lshlrev_b32_e32 v34, 16, v102
	v_pk_fma_f32 v[24:25], v[50:51], v[34:35], v[46:47]
	s_nop 0
	v_pk_fma_f32 v[24:25], v[42:43], v[66:67], v[24:25]
	s_nop 0
	v_pk_fma_f32 v[24:25], v[38:39], v[68:69], v[24:25]
	s_nop 0
	v_mul_f32_e32 v0, 0xbfb8aa3b, v25
	v_exp_f32_e32 v0, v0
	s_nop 0
	v_add_f32_e32 v0, 1.0, v0
	v_div_scale_f32 v26, s[6:7], v0, v0, 1.0
	v_rcp_f32_e32 v27, v26
	s_nop 0
	v_fma_f32 v68, -v26, v27, 1.0
	v_fmac_f32_e32 v27, v68, v27
	v_div_scale_f32 v68, vcc, 1.0, v0, 1.0
	v_mul_f32_e32 v69, v68, v27
	v_fma_f32 v74, -v26, v69, v68
	v_fmac_f32_e32 v69, v74, v27
	v_fma_f32 v26, -v26, v69, v68
	v_div_fmas_f32 v26, v26, v27, v69
	v_div_fixup_f32 v0, v26, v0, 1.0
	v_mul_f32_e32 v0, v25, v0
	v_mul_f32_e32 v0, v24, v0
	v_and_b32_e32 v25, 0xffff0000, v100
	v_and_b32_e32 v24, 0xffff0000, v102
	v_pk_fma_f32 v[26:27], v[12:13], v[24:25], v[16:17]
	s_nop 0
	v_pk_fma_f32 v[26:27], v[8:9], v[30:31], v[26:27]
	s_nop 0
	v_pk_fma_f32 v[26:27], v[4:5], v[28:29], v[26:27]
	s_nop 0
	v_mul_f32_e32 v20, 0xbfb8aa3b, v27
	v_exp_f32_e32 v20, v20
	s_nop 0
	v_add_f32_e32 v20, 1.0, v20
	v_div_scale_f32 v28, s[6:7], v20, v20, 1.0
	v_rcp_f32_e32 v29, v28
	s_nop 0
	v_fma_f32 v68, -v28, v29, 1.0
	v_fmac_f32_e32 v29, v68, v29
	v_div_scale_f32 v68, vcc, 1.0, v20, 1.0
	v_mul_f32_e32 v69, v68, v29
	v_fma_f32 v70, -v28, v69, v68
	v_fmac_f32_e32 v69, v70, v29
	v_fma_f32 v28, -v28, v69, v68
	v_div_fmas_f32 v28, v28, v29, v69
	v_div_fixup_f32 v20, v28, v20, 1.0
	v_mul_f32_e32 v20, v27, v20
	v_mul_f32_e32 v68, v26, v20
	v_lshlrev_b32_e32 v27, 16, v101
	v_lshlrev_b32_e32 v26, 16, v103
	v_pk_fma_f32 v[28:29], v[58:59], v[26:27], v[56:57]
	s_nop 0
	v_pk_fma_f32 v[28:29], v[54:55], v[64:65], v[28:29]
	s_nop 0
	v_pk_fma_f32 v[28:29], v[2:3], v[62:63], v[28:29]
	s_nop 0
	v_mul_f32_e32 v20, 0xbfb8aa3b, v29
	v_exp_f32_e32 v20, v20
	s_nop 0
	v_add_f32_e32 v20, 1.0, v20
	v_div_scale_f32 v62, s[6:7], v20, v20, 1.0
	v_rcp_f32_e32 v63, v62
	s_nop 0
	v_fma_f32 v69, -v62, v63, 1.0
	v_fmac_f32_e32 v63, v69, v63
	v_div_scale_f32 v69, vcc, 1.0, v20, 1.0
; DEVI float bf_lo(unsigned u) { return __uint_as_float(u << 16); }
; DEVI float bf_hi(unsigned u) { return __uint_as_float(u & 0xffff0000u); }
; DEVI float sigmoidf_(float x) { return 1.f / (1.f + __expf(-x)); }
; DEVI void st_bf4(bf16_t* p, f32x4 v) { u32x2 u; u.x = cvt_pk_bf16(v[0], v[1]); u.y = cvt_pk_bf16(v[2], v[3]); *(u32x2*)p = u; }
; __device__ void phase_conv(const Params& P, int l) {
;     ...
;     for (int t = 0; t < RC; ++t) {
;       const u32x2 gr = __builtin_nontemporal_load((const u32x2*)(up + (size_t)t * 11264)), vr = __builtin_nontemporal_load((const u32x2*)(up + (size_t)t * 11264 + DFF));
;       const f32x4 g0 = {bf_lo(gr.x), bf_hi(gr.x), bf_lo(gr.y), bf_hi(gr.y)}, v0 = {bf_lo(vr.x), bf_hi(vr.x), bf_lo(vr.y), bf_hi(vr.y)};
;       const f32x4 cgv = bg + wg2 * g0 + wg1 * g1 + wg0 * g2;
;       const f32x4 cvv = bv + wv2 * v0 + wv1 * v1 + wv0 * v2;
;       f32x4 o;
; #pragma unroll
;       for (int e = 0; e < 4; ++e) o[e] = cgv[e] * sigmoidf_(cgv[e]) * cvv[e];
;       st_bf4(ao + (size_t)t * DFF, o);
;       g2 = g1; g1 = g0; v2 = v1; v1 = v0;
	v_mul_f32_e32 v70, v69, v63
	v_fma_f32 v74, -v62, v70, v69
	v_fmac_f32_e32 v70, v74, v63
	v_fma_f32 v62, -v62, v70, v69
	v_div_fmas_f32 v62, v62, v63, v70
	v_div_fixup_f32 v20, v62, v20, 1.0
	v_mul_f32_e32 v20, v29, v20
	v_and_b32_e32 v63, 0xffff0000, v101
	v_and_b32_e32 v62, 0xffff0000, v103
	v_mul_f32_e32 v28, v28, v20
	v_pk_fma_f32 v[20:21], v[14:15], v[62:63], v[18:19]
	s_nop 0
	v_pk_fma_f32 v[20:21], v[10:11], v[32:33], v[20:21]
	s_nop 0
	v_pk_fma_f32 v[20:21], v[6:7], v[22:23], v[20:21]
	s_nop 0
	v_mul_f32_e32 v22, 0xbfb8aa3b, v21
	v_exp_f32_e32 v22, v22
	s_nop 0
	v_add_f32_e32 v22, 1.0, v22
	v_div_scale_f32 v23, s[6:7], v22, v22, 1.0
	v_rcp_f32_e32 v29, v23
	s_nop 0
	v_fma_f32 v69, -v23, v29, 1.0
	v_fmac_f32_e32 v29, v69, v29
	v_div_scale_f32 v69, vcc, 1.0, v22, 1.0
	v_mul_f32_e32 v70, v69, v29
	v_fma_f32 v71, -v23, v70, v69
	v_fmac_f32_e32 v70, v71, v29
	v_fma_f32 v23, -v23, v70, v69
	v_div_fmas_f32 v23, v23, v29, v70
	v_div_fixup_f32 v22, v23, v22, 1.0
	v_mul_f32_e32 v21, v21, v22
	v_add_co_u32_e32 v22, vcc, s3, v60
	v_mul_f32_e32 v21, v20, v21
	v_cvt_pk_bf16_f32 v20, v0, v68
	s_nop 0
	v_addc_co_u32_e32 v23, vcc, 0, v61, vcc
	s_mov_b32 s3, 0x1447d000
	v_cvt_pk_bf16_f32 v21, v28, v21
	global_store_dwordx2 v[22:23], v[20:21], off offset:3072
	v_add_co_u32_e32 v20, vcc, s3, v48
	s_mov_b32 s3, 0x1447f000
	s_nop 0
	v_addc_co_u32_e32 v21, vcc, 0, v49, vcc
	v_add_co_u32_e32 v22, vcc, s3, v48
	s_nop 0
	v_addc_co_u32_e32 v23, vcc, 0, v49, vcc
	s_mov_b32 s3, 0x1f46c000
	s_waitcnt vmcnt(9)
	v_lshlrev_b32_e32 v69, 16, v104
	s_waitcnt vmcnt(8)
	v_lshlrev_b32_e32 v68, 16, v106
	v_pk_fma_f32 v[28:29], v[50:51], v[68:69], v[46:47]
	s_nop 0
	v_pk_fma_f32 v[28:29], v[42:43], v[34:35], v[28:29]
	s_nop 0
	v_pk_fma_f32 v[28:29], v[38:39], v[66:67], v[28:29]
	s_nop 0
	v_mul_f32_e32 v0, 0xbfb8aa3b, v29
	v_exp_f32_e32 v0, v0
	s_nop 0
	v_add_f32_e32 v0, 1.0, v0
	v_div_scale_f32 v66, s[6:7], v0, v0, 1.0
	v_rcp_f32_e32 v67, v66
	s_nop 0
	v_fma_f32 v70, -v66, v67, 1.0
	v_fmac_f32_e32 v67, v70, v67
	v_div_scale_f32 v70, vcc, 1.0, v0, 1.0
	v_mul_f32_e32 v71, v70, v67
	v_fma_f32 v74, -v66, v71, v70
	v_fmac_f32_e32 v71, v74, v67
	v_fma_f32 v66, -v66, v71, v70
	v_div_fmas_f32 v66, v66, v67, v71
	v_div_fixup_f32 v0, v66, v0, 1.0
	v_mul_f32_e32 v0, v29, v0
	v_and_b32_e32 v67, 0xffff0000, v104
	v_and_b32_e32 v66, 0xffff0000, v106
	v_mul_f32_e32 v0, v28, v0
	v_pk_fma_f32 v[28:29], v[12:13], v[66:67], v[16:17]
	s_nop 0
	v_pk_fma_f32 v[28:29], v[8:9], v[24:25], v[28:29]
	s_nop 0
	v_pk_fma_f32 v[28:29], v[4:5], v[30:31], v[28:29]
	s_nop 0
	v_mul_f32_e32 v20, 0xbfb8aa3b, v29
	v_exp_f32_e32 v20, v20
	s_nop 0
	v_add_f32_e32 v20, 1.0, v20
	v_div_scale_f32 v22, s[6:7], v20, v20, 1.0
	v_rcp_f32_e32 v30, v22
	s_nop 0
	v_fma_f32 v31, -v22, v30, 1.0
	v_fmac_f32_e32 v30, v31, v30
	v_div_scale_f32 v31, vcc, 1.0, v20, 1.0
	v_mul_f32_e32 v70, v31, v30
	v_fma_f32 v71, -v22, v70, v31
	v_fmac_f32_e32 v70, v71, v30
	v_fma_f32 v22, -v22, v70, v31
	v_div_fmas_f32 v22, v22, v30, v70
	v_div_fixup_f32 v20, v22, v20, 1.0
	v_mul_f32_e32 v20, v29, v20
	v_lshlrev_b32_e32 v71, 16, v105
	v_lshlrev_b32_e32 v70, 16, v107
	v_mul_f32_e32 v76, v28, v20
	v_pk_fma_f32 v[28:29], v[58:59], v[70:71], v[56:57]
	s_nop 0
	v_pk_fma_f32 v[28:29], v[54:55], v[26:27], v[28:29]
	s_nop 0
	v_pk_fma_f32 v[28:29], v[2:3], v[64:65], v[28:29]
	s_nop 0
	v_mul_f32_e32 v20, 0xbfb8aa3b, v29
	v_exp_f32_e32 v20, v20
	s_nop 0
	v_add_f32_e32 v20, 1.0, v20
	v_div_scale_f32 v22, s[6:7], v20, v20, 1.0
	v_rcp_f32_e32 v30, v22
	s_nop 0
	v_fma_f32 v31, -v22, v30, 1.0
	v_fmac_f32_e32 v30, v31, v30
	v_div_scale_f32 v31, vcc, 1.0, v20, 1.0
	v_mul_f32_e32 v64, v31, v30
	v_fma_f32 v65, -v22, v64, v31
	v_fmac_f32_e32 v64, v65, v30
	v_fma_f32 v22, -v22, v64, v31
	v_div_fmas_f32 v22, v22, v30, v64
	v_and_b32_e32 v65, 0xffff0000, v105
	v_and_b32_e32 v64, 0xffff0000, v107
	v_pk_fma_f32 v[74:75], v[14:15], v[64:65], v[18:19]
	v_div_fixup_f32 v20, v22, v20, 1.0
	v_pk_fma_f32 v[74:75], v[10:11], v[62:63], v[74:75]
	v_mul_f32_e32 v20, v29, v20
	v_pk_fma_f32 v[32:33], v[6:7], v[32:33], v[74:75]
	v_mul_f32_e32 v77, v28, v20
	v_mul_f32_e32 v74, 0xbfb8aa3b, v33
	v_exp_f32_e32 v74, v74
	v_mov_b32_e32 v20, v69
	v_mov_b32_e32 v28, v68
	v_mov_b32_e32 v29, v66
	v_add_f32_e32 v74, 1.0, v74
	v_div_scale_f32 v75, s[6:7], v74, v74, 1.0
	v_rcp_f32_e32 v78, v75
	v_mov_b32_e32 v21, v67
	v_mov_b32_e32 v30, v70
	v_mov_b32_e32 v31, v64
	v_fma_f32 v79, -v75, v78, 1.0
	v_fmac_f32_e32 v78, v79, v78
	v_div_scale_f32 v79, vcc, 1.0, v74, 1.0
	v_mul_f32_e32 v80, v79, v78
	v_fma_f32 v81, -v75, v80, v79
	v_fmac_f32_e32 v80, v81, v78
	v_fma_f32 v75, -v75, v80, v79
	v_div_fmas_f32 v75, v75, v78, v80
	v_div_fixup_f32 v74, v75, v74, 1.0
	v_mul_f32_e32 v33, v33, v74
	v_add_co_u32_e32 v74, vcc, s3, v60
	v_mul_f32_e32 v33, v32, v33
	v_cvt_pk_bf16_f32 v32, v0, v76
	s_nop 0
	v_addc_co_u32_e32 v75, vcc, 0, v61, vcc
	s_mov_b32 s3, 0x14482000
	v_cvt_pk_bf16_f32 v33, v77, v33
	global_store_dwordx2 v[74:75], v[32:33], off offset:2048
	v_add_co_u32_e32 v32, vcc, s3, v48
	s_mov_b32 s3, 0x14485000
	s_nop 0
	v_addc_co_u32_e32 v33, vcc, 0, v49, vcc
	v_add_co_u32_e32 v32, vcc, s3, v48
	v_mov_b32_e32 v23, v65
	s_nop 0
	v_addc_co_u32_e32 v33, vcc, 0, v49, vcc
	v_mov_b32_e32 v22, v71
	s_waitcnt vmcnt(8)
; DEVI int lbid() { int t = __builtin_amdgcn_workgroup_id_x(); asm volatile("" : "+s"(t)); return t; }
; DEVI float bf_lo(unsigned u) { return __uint_as_float(u << 16); }
; DEVI float bf_hi(unsigned u) { return __uint_as_float(u & 0xffff0000u); }
; DEVI float sigmoidf_(float x) { return 1.f / (1.f + __expf(-x)); }
; DEVI f32x4 ld_bf4(const bf16_t* p) { u32x2 u = *(const u32x2*)p; return (f32x4){bf_lo(u.x), bf_hi(u.x), bf_lo(u.y), bf_hi(u.y)}; }
; DEVI void st_bf4(bf16_t* p, f32x4 v) { u32x2 u; u.x = cvt_pk_bf16(v[0], v[1]); u.y = cvt_pk_bf16(v[2], v[3]); *(u32x2*)p = u; }
; __device__ void phase_conv(const Params& P, int l) {
;     ...
;   for (int item = lbid() * 8 + wave; item < (T / RC) * NCG; item += gridDim.x * 8) {
;     const int cg = item % NCG, t0 = (item / NCG) * RC;
;     const int j = (cg * 64 + lane) * 4;
;     const f32x4 wg0 = *(const f32x4*)(cw + j), wg1 = *(const f32x4*)(cw + 11264 + j), wg2 = *(const f32x4*)(cw + 2 * 11264 + j), bg = *(const f32x4*)(cb + j);
;     const f32x4 wv0 = *(const f32x4*)(cw + DFF + j), wv1 = *(const f32x4*)(cw + 11264 + DFF + j), wv2 = *(const f32x4*)(cw + 2 * 11264 + DFF + j), bv = *(const f32x4*)(cb + DFF + j);
;     const bf16_t* up = UP + (size_t)t0 * 11264 + j;
;     f32x4 g1 = t0 >= 1 ? ld_bf4(up - 11264) : z4, g2 = t0 >= 2 ? ld_bf4(up - 2 * 11264) : z4;
;     f32x4 v1 = t0 >= 1 ? ld_bf4(up - 11264 + DFF) : z4, v2 = t0 >= 2 ? ld_bf4(up - 2 * 11264 + DFF) : z4;
;     bf16_t* ao = ACT + (size_t)t0 * DFF + j;
; #pragma unroll 8
;     for (int t = 0; t < RC; ++t) {
;       const u32x2 gr = __builtin_nontemporal_load((const u32x2*)(up + (size_t)t * 11264)), vr = __builtin_nontemporal_load((const u32x2*)(up + (size_t)t * 11264 + DFF));
;       const f32x4 g0 = {bf_lo(gr.x), bf_hi(gr.x), bf_lo(gr.y), bf_hi(gr.y)}, v0 = {bf_lo(vr.x), bf_hi(vr.x), bf_lo(vr.y), bf_hi(vr.y)};
;       const f32x4 cgv = bg + wg2 * g0 + wg1 * g1 + wg0 * g2;
;       const f32x4 cvv = bv + wv2 * v0 + wv1 * v1 + wv0 * v2;
;       f32x4 o;
; #pragma unroll
;       for (int e = 0; e < 4; ++e) o[e] = cgv[e] * sigmoidf_(cgv[e]) * cvv[e];
;       st_bf4(ao + (size_t)t * DFF, o);
;       g2 = g1; g1 = g0; v2 = v1; v1 = v0;
	v_lshlrev_b32_e32 v33, 16, v108
	s_waitcnt vmcnt(7)
	v_lshlrev_b32_e32 v32, 16, v110
	v_pk_fma_f32 v[76:77], v[50:51], v[32:33], v[46:47]
	s_nop 0
	v_pk_fma_f32 v[68:69], v[42:43], v[68:69], v[76:77]
	s_nop 0
	v_pk_fma_f32 v[34:35], v[38:39], v[34:35], v[68:69]
	s_nop 0
	v_mul_f32_e32 v0, 0xbfb8aa3b, v35
	v_exp_f32_e32 v0, v0
	s_nop 0
	v_add_f32_e32 v0, 1.0, v0
	v_div_scale_f32 v68, s[6:7], v0, v0, 1.0
	v_rcp_f32_e32 v69, v68
	s_nop 0
	v_fma_f32 v76, -v68, v69, 1.0
	v_fmac_f32_e32 v69, v76, v69
	v_div_scale_f32 v76, vcc, 1.0, v0, 1.0
	v_mul_f32_e32 v77, v76, v69
	v_fma_f32 v78, -v68, v77, v76
	v_fmac_f32_e32 v77, v78, v69
	v_fma_f32 v68, -v68, v77, v76
	v_div_fmas_f32 v68, v68, v69, v77
	v_div_fixup_f32 v0, v68, v0, 1.0
	v_mul_f32_e32 v0, v35, v0
	v_and_b32_e32 v69, 0xffff0000, v108
	v_and_b32_e32 v68, 0xffff0000, v110
	v_mul_f32_e32 v0, v34, v0
	v_pk_fma_f32 v[34:35], v[12:13], v[68:69], v[16:17]
	s_nop 0
	v_pk_fma_f32 v[34:35], v[8:9], v[66:67], v[34:35]
	s_nop 0
	v_pk_fma_f32 v[24:25], v[4:5], v[24:25], v[34:35]
	s_nop 0
	v_mul_f32_e32 v34, 0xbfb8aa3b, v25
	v_exp_f32_e32 v34, v34
	s_nop 0
	v_add_f32_e32 v34, 1.0, v34
	v_div_scale_f32 v35, s[6:7], v34, v34, 1.0
	v_rcp_f32_e32 v48, v35
	s_nop 0
	v_fma_f32 v66, -v35, v48, 1.0
	v_fmac_f32_e32 v48, v66, v48
	v_div_scale_f32 v66, vcc, 1.0, v34, 1.0
	v_mul_f32_e32 v67, v66, v48
	v_fma_f32 v74, -v35, v67, v66
	v_fmac_f32_e32 v67, v74, v48
	v_fma_f32 v35, -v35, v67, v66
	v_div_fmas_f32 v35, v35, v48, v67
	v_div_fixup_f32 v34, v35, v34, 1.0
	v_mul_f32_e32 v25, v25, v34
	v_lshlrev_b32_e32 v35, 16, v109
	v_lshlrev_b32_e32 v34, 16, v111
	v_mul_f32_e32 v74, v24, v25
	v_pk_fma_f32 v[24:25], v[58:59], v[34:35], v[56:57]
	s_nop 0
	v_pk_fma_f32 v[24:25], v[54:55], v[70:71], v[24:25]
	s_nop 0
	v_pk_fma_f32 v[24:25], v[2:3], v[26:27], v[24:25]
	s_nop 0
	v_mul_f32_e32 v26, 0xbfb8aa3b, v25
	v_exp_f32_e32 v26, v26
	s_nop 0
	v_add_f32_e32 v26, 1.0, v26
	v_div_scale_f32 v27, s[6:7], v26, v26, 1.0
	v_rcp_f32_e32 v48, v27
	s_nop 0
	v_fma_f32 v66, -v27, v48, 1.0
	v_fmac_f32_e32 v48, v66, v48
	v_div_scale_f32 v66, vcc, 1.0, v26, 1.0
	v_mul_f32_e32 v67, v66, v48
	v_fma_f32 v70, -v27, v67, v66
	v_fmac_f32_e32 v67, v70, v48
	v_fma_f32 v27, -v27, v67, v66
	v_div_fmas_f32 v27, v27, v48, v67
	v_and_b32_e32 v67, 0xffff0000, v109
	v_and_b32_e32 v66, 0xffff0000, v111
	v_pk_fma_f32 v[48:49], v[14:15], v[66:67], v[18:19]
	v_div_fixup_f32 v26, v27, v26, 1.0
	v_pk_fma_f32 v[48:49], v[10:11], v[64:65], v[48:49]
	v_mul_f32_e32 v25, v25, v26
	v_pk_fma_f32 v[48:49], v[6:7], v[62:63], v[48:49]
	v_mov_b32_e32 v26, v35
	v_mul_f32_e32 v62, 0xbfb8aa3b, v49
	v_exp_f32_e32 v62, v62
	v_mov_b32_e32 v35, v66
	v_mov_b32_e32 v27, v67
	v_mul_f32_e32 v70, v24, v25
	v_add_f32_e32 v62, 1.0, v62
	v_div_scale_f32 v63, s[6:7], v62, v62, 1.0
	v_rcp_f32_e32 v64, v63
	s_mov_b64 s[6:7], 0x16000
	v_lshl_add_u64 v[40:41], v[40:41], 0, s[6:7]
	s_mov_b64 s[6:7], 0x2c000
	v_fma_f32 v65, -v63, v64, 1.0
	v_fmac_f32_e32 v64, v65, v64
	v_div_scale_f32 v65, vcc, 1.0, v62, 1.0
	v_mul_f32_e32 v66, v65, v64
	v_fma_f32 v67, -v63, v66, v65
	v_fmac_f32_e32 v66, v67, v64
	v_fma_f32 v63, -v63, v66, v65
	v_div_fmas_f32 v63, v63, v64, v66
	v_div_fixup_f32 v62, v63, v62, 1.0
	v_mul_f32_e32 v49, v49, v62
	v_add_co_u32_e32 v60, vcc, 0x1f46f000, v60
	v_mov_b32_e32 v24, v33
	v_mov_b32_e32 v25, v69
	v_mov_b32_e32 v33, v68
	v_mul_f32_e32 v49, v48, v49
	v_addc_co_u32_e32 v61, vcc, 0, v61, vcc
	v_lshl_add_u64 v[44:45], v[44:45], 0, s[6:7]
	v_cvt_pk_bf16_f32 v48, v0, v74
	v_cvt_pk_bf16_f32 v49, v70, v49
	global_store_dwordx2 v[60:61], v[48:49], off offset:1024
	s_cbranch_scc0 .LBB0_28
	v_readlane_b32 s2, v252, 8
	s_nop 1
	v_add_u32_e32 v72, s2, v72
	s_movk_i32 s2, 0x15ff
	v_cmp_lt_i32_e32 vcc, s2, v72
	s_or_b64 s[0:1], vcc, s[0:1]
	s_andn2_b64 exec, exec, s[0:1]
	s_cbranch_execnz .LBB0_19
